# selected/window attention softmax: 0.125 scale and log2(e) folded into one f32 fma per score (exp2(s*c - m*log2e)), one VALU op less per element; still f32
# speedup vs baseline: 1.0060x; 1.0004x over previous
; DI float quad_max(float v) { v = fmaxf(v, __shfl_xor(v, 16)); v = fmaxf(v, __shfl_xor(v, 32)); return v; }
; DI void softmax_tile_full(f32x4 (&st)[4], float& m, float& l, f32x4 (&ot)[4]) {
;   float tm = st[0][0];
; #pragma unroll
;   for (int mt = 0; mt < 4; ++mt)
; #pragma unroll
;     for (int j = 0; j < 4; ++j) tm = fmaxf(tm, st[mt][j]);
;   tm = quad_max(tm) * 0.125f;
;   const float mn = fmaxf(m, tm);
;   const float alpha = __expf(m - mn);
;   float ps = 0.f;
; #pragma unroll
;   for (int mt = 0; mt < 4; ++mt)
; #pragma unroll
;     for (int j = 0; j < 4; ++j) { const float p = __expf(st[mt][j] * 0.125f - mn); st[mt][j] = p; ps += p; }
;   l = l * alpha + ps;
;   m = mn;
; DI void sel_attn_item(const Params& P, int it, u16* sQ, u16* sKunused, u16* sVunused) {
;     ...
;     for (int qt = 0; qt < 2; ++qt) {
;       f32x4 st[4];
;       st_mma(st, sK, bq[qt], lane);
;       const bool selq = (mysel[qt] >> kb) & 1ull;
;       if (__ballot(selq) == ~0ull && kb * 64 + 63 <= t0 + 16 * qt) softmax_tile_full(st, m[qt], lsum[qt], ot[qt]);
.LBB0_246:
	v_add_u32_e32 v5, 0x7000, v211
	ds_read_b128 v[124:127], v173 offset:18432
	ds_read_b128 v[128:131], v173 offset:18496
	ds_read_b128 v[132:135], v173 offset:20736
	ds_read_b128 v[136:139], v173 offset:20800
	ds_read_b128 v[140:143], v173 offset:23040
	ds_read_b128 v[120:123], v173 offset:23104
	ds_read_b128 v[116:119], v210 offset:18432
	ds_read_b128 v[112:115], v210 offset:18496
	ds_read2_b64 v[0:3], v5 offset0:160 offset1:164
	s_waitcnt lgkmcnt(8)
	v_mfma_f32_16x16x32_bf16 v[6:9], v[124:127], v[48:51], 0
	v_add_u32_e32 v15, 0x6800, v212
	v_lshlrev_b64 v[180:181], v4, 1
	v_add_u32_e32 v14, 0x6800, v211
	s_waitcnt lgkmcnt(0)
	v_mov_b64_e32 v[104:105], v[2:3]
	v_mov_b64_e32 v[106:107], v[0:1]
	ds_read2_b64 v[0:3], v5 offset0:168 offset1:172
	v_mfma_f32_16x16x32_bf16 v[156:159], v[128:131], v[52:55], v[6:9]
	v_add_u32_e32 v80, 0x7800, v211
	ds_read2_b64 v[108:111], v14 offset0:128 offset1:132
	ds_read2_b64 v[100:103], v80 offset0:200 offset1:204
	ds_read2_b64 v[6:9], v15 offset0:136 offset1:140
	v_mfma_f32_16x16x32_bf16 v[10:13], v[132:135], v[48:51], 0
	s_waitcnt lgkmcnt(3)
	v_mov_b64_e32 v[88:89], v[2:3]
	v_mov_b64_e32 v[90:91], v[0:1]
	v_lshlrev_b32_e32 v222, 6, v4
	v_mfma_f32_16x16x32_bf16 v[0:3], v[116:119], v[48:51], 0
	s_waitcnt lgkmcnt(0)
	v_mov_b64_e32 v[96:97], v[8:9]
	v_mov_b64_e32 v[98:99], v[6:7]
	v_or_b32_e32 v233, 63, v222
	v_mfma_f32_16x16x32_bf16 v[6:9], v[140:143], v[48:51], 0
	v_cmp_gt_i32_e32 vcc, v233, v170
	v_mfma_f32_16x16x32_bf16 v[152:155], v[136:139], v[52:55], v[10:13]
	ds_read2_b64 v[92:95], v14 offset0:136 offset1:140
	s_nop 1
	ds_read2_b64 v[10:13], v15 offset0:128 offset1:132
	ds_read2_b64 v[84:87], v80 offset0:192 offset1:196
	s_waitcnt lgkmcnt(1)
	v_mov_b64_e32 v[82:83], v[10:11]
	v_mfma_f32_16x16x32_bf16 v[144:147], v[112:115], v[52:55], v[0:3]
	v_mov_b64_e32 v[80:81], v[12:13]
	s_nop 1
	v_and_b32_e32 v1, v181, v175
	v_and_b32_e32 v0, v180, v174
	v_cmp_ne_u64_e64 s[0:1], 0, v[0:1]
	v_mfma_f32_16x16x32_bf16 v[148:151], v[120:123], v[52:55], v[6:9]
	s_cmp_lg_u64 s[0:1], -1
	s_cselect_b64 s[2:3], -1, 0
	s_or_b64 s[4:5], s[2:3], vcc
	s_mov_b64 s[2:3], -1
	s_and_b64 vcc, exec, s[4:5]
	s_cbranch_vccnz .LBB0_248
	v_max_f32_e32 v0, v157, v157
	v_max_f32_e32 v1, v156, v156
	v_max_f32_e32 v0, v1, v0
	v_max3_f32 v0, v0, v158, v159
	v_max3_f32 v0, v0, v152, v153
	v_mbcnt_hi_u32_b32 v1, -1, v184
	v_max3_f32 v0, v0, v154, v155
	v_and_b32_e32 v3, 64, v1
	v_max3_f32 v0, v0, v148, v149
	v_xor_b32_e32 v2, 16, v1
	v_add_u32_e32 v3, 64, v3
	v_max3_f32 v0, v0, v150, v151
	v_cmp_lt_i32_e32 vcc, v2, v3
	v_max3_f32 v0, v0, v144, v145
	v_max3_f32 v0, v0, v146, v147
	v_cndmask_b32_e32 v2, v1, v2, vcc
	v_lshlrev_b32_e32 v2, 2, v2
	ds_bpermute_b32 v2, v2, v0
	s_mov_b64 s[2:3], 0
	s_waitcnt lgkmcnt(0)
	v_max_f32_e32 v2, v2, v2
	v_max_f32_e32 v0, v0, v2
	v_xor_b32_e32 v2, 32, v1
	v_cmp_lt_i32_e32 vcc, v2, v3
	s_nop 1
	v_cndmask_b32_e32 v1, v1, v2, vcc
	v_lshlrev_b32_e32 v1, 2, v1
	ds_bpermute_b32 v1, v1, v0
	s_waitcnt lgkmcnt(0)
	v_max_f32_e32 v1, v1, v1
	v_max_f32_e32 v0, v0, v1
	v_mul_f32_e32 v0, 0x3e000000, v0
	v_max_f32_e32 v1, v221, v221
	v_max_f32_e32 v220, v1, v0
	v_mul_f32_e32 v254, 0xbfb8aa3b, v220
	v_fmamk_f32 v0, v156, 0x3e38aa3b, v254
	v_fmamk_f32 v1, v157, 0x3e38aa3b, v254
	v_exp_f32_e32 v0, v0
	v_fmamk_f32 v2, v158, 0x3e38aa3b, v254
	v_exp_f32_e32 v1, v1
	v_fmamk_f32 v3, v159, 0x3e38aa3b, v254
	v_exp_f32_e32 v2, v2
	v_exp_f32_e32 v3, v3
	v_add_f32_e32 v4, 0, v0
	v_add_f32_e32 v4, v1, v4
	v_add_f32_e32 v4, v2, v4
	v_add_f32_e32 v8, v3, v4
	v_fmamk_f32 v4, v152, 0x3e38aa3b, v254
	v_fmamk_f32 v5, v153, 0x3e38aa3b, v254
	v_exp_f32_e32 v4, v4
	v_fmamk_f32 v6, v154, 0x3e38aa3b, v254
	v_exp_f32_e32 v5, v5
	v_fmamk_f32 v7, v155, 0x3e38aa3b, v254
	v_exp_f32_e32 v6, v6
	v_exp_f32_e32 v7, v7
	v_add_f32_e32 v8, v4, v8
	v_add_f32_e32 v8, v5, v8
	v_add_f32_e32 v8, v6, v8
	v_add_f32_e32 v12, v7, v8
	v_fmamk_f32 v8, v148, 0x3e38aa3b, v254
	v_fmamk_f32 v9, v149, 0x3e38aa3b, v254
	v_exp_f32_e32 v8, v8
	v_fmamk_f32 v10, v150, 0x3e38aa3b, v254
	v_exp_f32_e32 v9, v9
	v_fmamk_f32 v11, v151, 0x3e38aa3b, v254
	v_exp_f32_e32 v10, v10
	v_exp_f32_e32 v11, v11
	v_add_f32_e32 v12, v8, v12
	v_add_f32_e32 v12, v9, v12
	v_add_f32_e32 v12, v10, v12
	v_add_f32_e32 v162, v11, v12
	v_fmamk_f32 v12, v144, 0x3e38aa3b, v254
	v_fmamk_f32 v13, v145, 0x3e38aa3b, v254
	v_exp_f32_e32 v12, v12
	v_fmamk_f32 v14, v146, 0x3e38aa3b, v254
	v_exp_f32_e32 v13, v13
	v_fmamk_f32 v15, v147, 0x3e38aa3b, v254
	v_exp_f32_e32 v14, v14
	v_exp_f32_e32 v15, v15
	v_add_f32_e32 v162, v12, v162
	v_add_f32_e32 v162, v13, v162
	v_add_f32_e32 v162, v14, v162
	v_add_f32_e32 v162, v15, v162
; DI float quad_max(float v) { v = fmaxf(v, __shfl_xor(v, 16)); v = fmaxf(v, __shfl_xor(v, 32)); return v; }
; DI void softmax_tile(f32x4 (&st)[4], const bool (&msk)[4][4], float& m, float& l, f32x4 (&ot)[4]) {
;   float tm = -1e30f;
; #pragma unroll
;   for (int mt = 0; mt < 4; ++mt)
; #pragma unroll
;     for (int j = 0; j < 4; ++j) { float s = st[mt][j] * 0.125f; st[mt][j] = s; if (msk[mt][j]) tm = fmaxf(tm, s); }
;   tm = quad_max(tm);
;   float mn = fmaxf(m, tm);
;   float alpha = __expf(m - mn);
;   float ps = 0.f;
; #pragma unroll
;   for (int mt = 0; mt < 4; ++mt)
; #pragma unroll
;     for (int j = 0; j < 4; ++j) { float p = msk[mt][j] ? __expf(st[mt][j] - mn) : 0.f; st[mt][j] = p; ps += p; }
;   l = l * alpha + ps;
;   m = mn;
; DI void sel_attn_item(const Params& P, int it, u16* sQ, u16* sKunused, u16* sVunused) {
;     ...
;       else {
;         bool msk[4][4];
; #pragma unroll
;         for (int mt = 0; mt < 4; ++mt)
; #pragma unroll
;           for (int j = 0; j < 4; ++j) { int s = kb * 64 + 16 * mt + 4 * quad + j; msk[mt][j] = selq && (s <= tq[qt]); }
;         softmax_tile(st, msk, m[qt], lsum[qt], ot[qt]);
.LBB0_248:
	v_or_b32_e32 v226, v222, v209
	v_or_b32_e32 v232, 2, v226
	v_or_b32_e32 v231, 3, v226
	v_or_b32_e32 v230, 16, v226
	v_or_b32_e32 v229, 17, v226
	v_or_b32_e32 v228, 18, v226
	v_or_b32_e32 v227, 19, v226
	v_or_b32_e32 v225, 32, v226
	v_or_b32_e32 v224, 33, v226
	v_or_b32_e32 v223, 34, v226
	v_or_b32_e32 v222, 35, v226
	s_andn2_b64 vcc, exec, s[2:3]
	v_cmp_le_i32_e64 s[8:9], v226, v172
	v_cmp_lt_i32_e64 s[14:15], v226, v172
	v_cmp_le_i32_e64 s[20:21], v232, v172
	v_cmp_le_i32_e64 s[26:27], v231, v172
	v_cmp_le_i32_e64 s[24:25], v230, v172
	v_cmp_le_i32_e64 s[10:11], v229, v172
	v_cmp_le_i32_e64 s[18:19], v228, v172
	v_cmp_le_i32_e64 s[22:23], v227, v172
	v_cmp_le_i32_e64 s[4:5], v225, v172
	v_cmp_le_i32_e64 s[12:13], v224, v172
	v_cmp_le_i32_e64 s[16:17], v223, v172
	v_cmp_le_i32_e64 s[6:7], v222, v172
	s_cbranch_vccnz .LBB0_250
	v_or_b32_e32 v0, 48, v226
	v_cmp_le_i32_e64 s[2:3], v0, v172
	v_or_b32_e32 v0, 49, v226
	v_cmp_le_i32_e64 s[30:31], v0, v172
	v_or_b32_e32 v0, 50, v226
	v_cmp_le_i32_e64 s[34:35], v0, v172
	v_or_b32_e32 v0, 51, v226
	v_cmp_le_i32_e64 s[36:37], v0, v172
	v_mul_f32_e32 v0, 0x3e000000, v156
	v_max_f32_e32 v0, 0xf149f2ca, v0
	s_and_b64 s[8:9], s[0:1], s[8:9]
	v_cndmask_b32_e64 v0, v186, v0, s[8:9]
	v_mul_f32_e32 v1, 0x3e000000, v157
	v_max_f32_e32 v1, v0, v1
	s_and_b64 s[14:15], s[0:1], s[14:15]
	v_cndmask_b32_e64 v0, v0, v1, s[14:15]
	v_mul_f32_e32 v1, 0x3e000000, v158
	v_max_f32_e32 v1, v0, v1
	s_and_b64 s[20:21], s[0:1], s[20:21]
	v_cndmask_b32_e64 v0, v0, v1, s[20:21]
	v_mul_f32_e32 v1, 0x3e000000, v159
	v_max_f32_e32 v1, v0, v1
	s_and_b64 s[26:27], s[0:1], s[26:27]
	v_cndmask_b32_e64 v0, v0, v1, s[26:27]
	v_mul_f32_e32 v1, 0x3e000000, v152
	v_max_f32_e32 v1, v0, v1
	s_and_b64 vcc, s[0:1], s[24:25]
	v_cndmask_b32_e32 v0, v0, v1, vcc
	v_mul_f32_e32 v1, 0x3e000000, v153
	v_max_f32_e32 v2, v0, v0
	v_max_f32_e32 v1, v2, v1
	s_and_b64 s[10:11], s[0:1], s[10:11]
	v_cndmask_b32_e64 v0, v0, v1, s[10:11]
	v_mul_f32_e32 v1, 0x3e000000, v154
	v_max_f32_e32 v2, v0, v0
	v_max_f32_e32 v1, v2, v1
	s_and_b64 s[18:19], s[0:1], s[18:19]
	v_cndmask_b32_e64 v0, v0, v1, s[18:19]
	v_mul_f32_e32 v1, 0x3e000000, v155
	v_max_f32_e32 v2, v0, v0
	v_max_f32_e32 v1, v2, v1
	s_and_b64 s[24:25], s[0:1], s[22:23]
	v_cndmask_b32_e64 v0, v0, v1, s[24:25]
	v_mul_f32_e32 v1, 0x3e000000, v148
	v_max_f32_e32 v2, v0, v0
	v_max_f32_e32 v1, v2, v1
	s_and_b64 s[4:5], s[0:1], s[4:5]
	v_cndmask_b32_e64 v0, v0, v1, s[4:5]
	v_mul_f32_e32 v1, 0x3e000000, v149
	v_max_f32_e32 v2, v0, v0
	v_max_f32_e32 v1, v2, v1
	s_and_b64 s[12:13], s[0:1], s[12:13]
	v_cndmask_b32_e64 v0, v0, v1, s[12:13]
	v_mul_f32_e32 v1, 0x3e000000, v150
	v_max_f32_e32 v2, v0, v0
	v_max_f32_e32 v1, v2, v1
	s_and_b64 s[22:23], s[0:1], s[16:17]
	v_cndmask_b32_e64 v0, v0, v1, s[22:23]
	v_mul_f32_e32 v1, 0x3e000000, v151
	v_max_f32_e32 v2, v0, v0
	v_max_f32_e32 v1, v2, v1
	s_and_b64 s[38:39], s[0:1], s[6:7]
	v_cndmask_b32_e64 v0, v0, v1, s[38:39]
	v_mul_f32_e32 v1, 0x3e000000, v144
	v_max_f32_e32 v2, v0, v0
	v_max_f32_e32 v1, v2, v1
	s_and_b64 s[6:7], s[0:1], s[2:3]
	v_cndmask_b32_e64 v0, v0, v1, s[6:7]
	v_mul_f32_e32 v1, 0x3e000000, v145
	v_max_f32_e32 v2, v0, v0
	v_max_f32_e32 v1, v2, v1
	s_and_b64 s[16:17], s[0:1], s[30:31]
	v_cndmask_b32_e64 v0, v0, v1, s[16:17]
	v_mul_f32_e32 v1, 0x3e000000, v146
	v_max_f32_e32 v2, v0, v0
	v_max_f32_e32 v1, v2, v1
	s_and_b64 s[2:3], s[0:1], s[34:35]
	v_cndmask_b32_e64 v0, v0, v1, s[2:3]
	v_mul_f32_e32 v1, 0x3e000000, v147
	v_max_f32_e32 v2, v0, v0
	v_max_f32_e32 v1, v2, v1
	s_and_b64 s[0:1], s[0:1], s[36:37]
	v_cndmask_b32_e64 v0, v0, v1, s[0:1]
	v_mbcnt_hi_u32_b32 v1, -1, v184
	v_and_b32_e32 v3, 64, v1
	v_xor_b32_e32 v2, 16, v1
	v_add_u32_e32 v3, 64, v3
	v_cmp_lt_i32_e64 s[30:31], v2, v3
	s_nop 1
	v_cndmask_b32_e64 v2, v1, v2, s[30:31]
	v_lshlrev_b32_e32 v2, 2, v2
	ds_bpermute_b32 v2, v2, v0
	v_max_f32_e32 v0, v0, v0
	s_waitcnt lgkmcnt(0)
	v_max_f32_e32 v2, v2, v2
	v_max_f32_e32 v0, v0, v2
	v_xor_b32_e32 v2, 32, v1
	v_cmp_lt_i32_e64 s[30:31], v2, v3
	s_nop 1
	v_cndmask_b32_e64 v1, v1, v2, s[30:31]
	v_lshlrev_b32_e32 v1, 2, v1
	ds_bpermute_b32 v1, v1, v0
	s_waitcnt lgkmcnt(0)
	v_max3_f32 v220, v221, v0, v1
	v_mul_f32_e32 v254, 0xbfb8aa3b, v220
	v_fmamk_f32 v0, v156, 0x3e38aa3b, v254
	v_fmamk_f32 v1, v157, 0x3e38aa3b, v254
	v_exp_f32_e32 v0, v0
	v_fmamk_f32 v2, v158, 0x3e38aa3b, v254
	v_exp_f32_e32 v1, v1
	v_fmamk_f32 v3, v159, 0x3e38aa3b, v254
	v_exp_f32_e32 v2, v2
	v_fmamk_f32 v4, v152, 0x3e38aa3b, v254
	v_exp_f32_e32 v3, v3
	v_fmamk_f32 v5, v153, 0x3e38aa3b, v254
	v_cndmask_b32_e64 v0, 0, v0, s[8:9]
	v_exp_f32_e32 v4, v4
	v_fmamk_f32 v6, v154, 0x3e38aa3b, v254
	v_cndmask_b32_e64 v1, 0, v1, s[14:15]
	v_exp_f32_e32 v5, v5
	v_fmamk_f32 v7, v155, 0x3e38aa3b, v254
	v_fmamk_f32 v12, v144, 0x3e38aa3b, v254
	v_add_f32_e32 v144, 0, v0
	v_cndmask_b32_e64 v2, 0, v2, s[20:21]
	v_exp_f32_e32 v6, v6
	v_fmamk_f32 v8, v148, 0x3e38aa3b, v254
	v_add_f32_e32 v144, v1, v144
	v_cndmask_b32_e64 v3, 0, v3, s[26:27]
	v_exp_f32_e32 v7, v7
	v_fmamk_f32 v9, v149, 0x3e38aa3b, v254
	v_add_f32_e32 v144, v2, v144
	v_cndmask_b32_e32 v4, 0, v4, vcc
	v_exp_f32_e32 v8, v8
	v_fmamk_f32 v10, v150, 0x3e38aa3b, v254
	v_add_f32_e32 v144, v3, v144
	v_cndmask_b32_e64 v5, 0, v5, s[10:11]
	v_exp_f32_e32 v9, v9
	v_fmamk_f32 v11, v151, 0x3e38aa3b, v254
	v_add_f32_e32 v144, v4, v144
	v_cndmask_b32_e64 v6, 0, v6, s[18:19]
	v_exp_f32_e32 v10, v10
	v_add_f32_e32 v144, v5, v144
	v_cndmask_b32_e64 v7, 0, v7, s[24:25]
	v_exp_f32_e32 v11, v11
	v_fmamk_f32 v13, v145, 0x3e38aa3b, v254
	v_add_f32_e32 v144, v6, v144
	v_cndmask_b32_e64 v8, 0, v8, s[4:5]
	v_exp_f32_e32 v12, v12
	v_fmamk_f32 v14, v146, 0x3e38aa3b, v254
	v_add_f32_e32 v144, v7, v144
	v_cndmask_b32_e64 v9, 0, v9, s[12:13]
	v_exp_f32_e32 v13, v13
	v_fmamk_f32 v15, v147, 0x3e38aa3b, v254
	v_add_f32_e32 v144, v8, v144
	v_cndmask_b32_e64 v10, 0, v10, s[22:23]
	v_exp_f32_e32 v14, v14
	v_add_f32_e32 v144, v9, v144
	v_cndmask_b32_e64 v11, 0, v11, s[38:39]
	v_exp_f32_e32 v15, v15
	v_add_f32_e32 v144, v10, v144
	v_cndmask_b32_e64 v12, 0, v12, s[6:7]
	v_add_f32_e32 v144, v11, v144
	v_cndmask_b32_e64 v13, 0, v13, s[16:17]
	v_add_f32_e32 v144, v12, v144
	v_cndmask_b32_e64 v14, 0, v14, s[2:3]
	v_add_f32_e32 v144, v13, v144
	v_cndmask_b32_e64 v15, 0, v15, s[0:1]
	v_add_f32_e32 v144, v14, v144
	v_add_f32_e32 v162, v15, v144
; DI unsigned pk2(float a, float b) { f32x2_t v = {a, b}; bf16x2_t r = __builtin_convertvector(v, bf16x2_t); return __builtin_bit_cast(unsigned, r); }
; DI float quad_max(float v) { v = fmaxf(v, __shfl_xor(v, 16)); v = fmaxf(v, __shfl_xor(v, 32)); return v; }
; DI void pv_mma(f32x4 (&ot)[4], const u16* sVt, const f32x4 (&p)[4], int lane) {
;   const int r = lane & 15, quad = lane >> 4;
; #pragma unroll
;   for (int ks = 0; ks < 2; ++ks) {
;     uint4 pu;
;     pu.x = pk2(p[2 * ks][0], p[2 * ks][1]); pu.y = pk2(p[2 * ks][2], p[2 * ks][3]);
;     pu.z = pk2(p[2 * ks + 1][0], p[2 * ks + 1][1]); pu.w = pk2(p[2 * ks + 1][2], p[2 * ks + 1][3]);
;     bf16x8 pb = __builtin_bit_cast(bf16x8, pu);
; #pragma unroll
;     for (int dt = 0; dt < 4; ++dt) {
;       const u16* vrow = sVt + (16 * dt + r) * 72;
;       s16x4 lo = *(const s16x4*)(vrow + ((32 * ks + 4 * quad) ^ (16 * dt)));
;       s16x4 hi = *(const s16x4*)(vrow + ((32 * ks + 16 + 4 * quad) ^ (16 * dt)));
;       bf16x8 vf = __builtin_shufflevector(lo, hi, 0, 1, 2, 3, 4, 5, 6, 7);
;       ot[dt] = __builtin_amdgcn_mfma_f32_16x16x32_bf16(vf, pb, ot[dt], 0, 0, 0);
;     }
;   }
; DI void softmax_tile_full(f32x4 (&st)[4], float& m, float& l, f32x4 (&ot)[4]) {
;   float tm = st[0][0];
; #pragma unroll
;   for (int mt = 0; mt < 4; ++mt)
; #pragma unroll
;     for (int j = 0; j < 4; ++j) tm = fmaxf(tm, st[mt][j]);
;   tm = quad_max(tm) * 0.125f;
;   const float mn = fmaxf(m, tm);
;   const float alpha = __expf(m - mn);
;   float ps = 0.f;
; #pragma unroll
;   for (int mt = 0; mt < 4; ++mt)
; #pragma unroll
;     for (int j = 0; j < 4; ++j) { const float p = __expf(st[mt][j] * 0.125f - mn); st[mt][j] = p; ps += p; }
;   l = l * alpha + ps;
;   m = mn;
; #pragma unroll
;   for (int dt = 0; dt < 4; ++dt)
; #pragma unroll
;     for (int j = 0; j < 4; ++j) ot[dt][j] *= alpha;
.LBB0_250:
	v_sub_f32_e32 v144, v221, v220
	v_mul_f32_e32 v144, 0x3fb8aa3b, v144
	v_exp_f32_e32 v144, v144
	v_cvt_pk_bf16_f32 v0, v0, v1
	v_cvt_pk_bf16_f32 v1, v2, v3
	v_cvt_pk_bf16_f32 v2, v4, v5
	v_pk_mul_f32 v[46:47], v[46:47], v[144:145] op_sel_hi:[1,0]
	v_pk_mul_f32 v[44:45], v[44:45], v[144:145] op_sel_hi:[1,0]
	v_cvt_pk_bf16_f32 v3, v6, v7
	v_pk_mul_f32 v[42:43], v[42:43], v[144:145] op_sel_hi:[1,0]
	v_pk_mul_f32 v[40:41], v[40:41], v[144:145] op_sel_hi:[1,0]
	v_pk_mul_f32 v[38:39], v[38:39], v[144:145] op_sel_hi:[1,0]
	v_pk_mul_f32 v[36:37], v[36:37], v[144:145] op_sel_hi:[1,0]
	v_pk_mul_f32 v[34:35], v[34:35], v[144:145] op_sel_hi:[1,0]
	v_pk_mul_f32 v[32:33], v[32:33], v[144:145] op_sel_hi:[1,0]
	v_mfma_f32_16x16x32_bf16 v[4:7], v[108:111], v[0:3], v[44:47]
	v_cvt_pk_bf16_f32 v8, v8, v9
	v_cvt_pk_bf16_f32 v9, v10, v11
	v_cvt_pk_bf16_f32 v10, v12, v13
	v_mfma_f32_16x16x32_bf16 v[40:43], v[104:107], v[0:3], v[40:43]
	v_cvt_pk_bf16_f32 v11, v14, v15
	v_cmp_gt_i32_e32 vcc, v233, v213
	v_mfma_f32_16x16x32_bf16 v[36:39], v[100:103], v[0:3], v[36:39]
	v_mfma_f32_16x16x32_bf16 v[0:3], v[96:99], v[0:3], v[32:35]
	v_mfma_f32_16x16x32_bf16 v[32:35], v[80:83], v[8:11], v[0:3]
	v_mfma_f32_16x16x32_bf16 v[0:3], v[124:127], v[56:59], 0
	v_mfma_f32_16x16x32_bf16 v[128:131], v[128:131], v[60:63], v[0:3]
	v_mfma_f32_16x16x32_bf16 v[0:3], v[132:135], v[56:59], 0
	v_mfma_f32_16x16x32_bf16 v[124:127], v[136:139], v[60:63], v[0:3]
	v_mfma_f32_16x16x32_bf16 v[0:3], v[140:143], v[56:59], 0
	v_mfma_f32_16x16x32_bf16 v[132:135], v[116:119], v[56:59], 0
	v_mfma_f32_16x16x32_bf16 v[44:47], v[92:95], v[8:11], v[4:7]
	s_nop 2
	v_and_b32_e32 v5, v181, v177
	v_and_b32_e32 v4, v180, v176
	v_cmp_ne_u64_e64 s[0:1], 0, v[4:5]
	v_mfma_f32_16x16x32_bf16 v[40:43], v[88:91], v[8:11], v[40:43]
	s_cmp_lg_u64 s[0:1], -1
	s_cselect_b64 s[2:3], -1, 0
	s_or_b64 s[4:5], s[2:3], vcc
	s_waitcnt lgkmcnt(0)
	v_mfma_f32_16x16x32_bf16 v[36:39], v[84:87], v[8:11], v[36:39]
	s_mov_b64 s[2:3], -1
	s_and_b64 vcc, exec, s[4:5]
	v_mfma_f32_16x16x32_bf16 v[120:123], v[120:123], v[60:63], v[0:3]
	v_mfma_f32_16x16x32_bf16 v[112:115], v[112:115], v[60:63], v[132:135]
	s_cbranch_vccnz .LBB0_252
	s_nop 0
	v_max_f32_e32 v0, v129, v129
	v_max_f32_e32 v1, v128, v128
	v_max_f32_e32 v0, v1, v0
	v_max3_f32 v0, v0, v130, v131
	v_max3_f32 v0, v0, v124, v125
	v_mbcnt_hi_u32_b32 v1, -1, v184
	v_max3_f32 v0, v0, v126, v127
	v_and_b32_e32 v3, 64, v1
	v_max3_f32 v0, v0, v120, v121
	v_xor_b32_e32 v2, 16, v1
	v_add_u32_e32 v3, 64, v3
	v_max3_f32 v0, v0, v122, v123
	v_cmp_lt_i32_e32 vcc, v2, v3
	v_max3_f32 v0, v0, v112, v113
	v_max3_f32 v0, v0, v114, v115
	v_cndmask_b32_e32 v2, v1, v2, vcc
	v_lshlrev_b32_e32 v2, 2, v2
	ds_bpermute_b32 v2, v2, v0
	s_mov_b64 s[2:3], 0
	s_waitcnt lgkmcnt(0)
	v_max_f32_e32 v2, v2, v2
	v_max_f32_e32 v0, v0, v2
	v_xor_b32_e32 v2, 32, v1
	v_cmp_lt_i32_e32 vcc, v2, v3
	s_nop 1
	v_cndmask_b32_e32 v1, v1, v2, vcc
	v_lshlrev_b32_e32 v1, 2, v1
	ds_bpermute_b32 v1, v1, v0
	s_waitcnt lgkmcnt(0)
	v_max_f32_e32 v1, v1, v1
	v_max_f32_e32 v0, v0, v1
	v_mul_f32_e32 v0, 0x3e000000, v0
	v_max_f32_e32 v1, v218, v218
	v_max_f32_e32 v117, v1, v0
	v_mul_f32_e32 v255, 0xbfb8aa3b, v117
	v_fmamk_f32 v0, v128, 0x3e38aa3b, v255
	v_fmamk_f32 v1, v129, 0x3e38aa3b, v255
	v_exp_f32_e32 v0, v0
	v_fmamk_f32 v2, v130, 0x3e38aa3b, v255
	v_exp_f32_e32 v1, v1
	v_fmamk_f32 v3, v131, 0x3e38aa3b, v255
	v_exp_f32_e32 v2, v2
	v_exp_f32_e32 v3, v3
	v_add_f32_e32 v4, 0, v0
	v_add_f32_e32 v4, v1, v4
	v_add_f32_e32 v4, v2, v4
	v_add_f32_e32 v8, v3, v4
	v_fmamk_f32 v4, v124, 0x3e38aa3b, v255
	v_fmamk_f32 v5, v125, 0x3e38aa3b, v255
	v_exp_f32_e32 v4, v4
	v_fmamk_f32 v6, v126, 0x3e38aa3b, v255
	v_exp_f32_e32 v5, v5
	v_fmamk_f32 v7, v127, 0x3e38aa3b, v255
	v_exp_f32_e32 v6, v6
	v_exp_f32_e32 v7, v7
	v_add_f32_e32 v8, v4, v8
	v_add_f32_e32 v8, v5, v8
	v_add_f32_e32 v8, v6, v8
	v_add_f32_e32 v12, v7, v8
	v_fmamk_f32 v8, v120, 0x3e38aa3b, v255
	v_fmamk_f32 v9, v121, 0x3e38aa3b, v255
	v_exp_f32_e32 v8, v8
	v_fmamk_f32 v10, v122, 0x3e38aa3b, v255
	v_exp_f32_e32 v9, v9
	v_fmamk_f32 v11, v123, 0x3e38aa3b, v255
	v_exp_f32_e32 v10, v10
	v_exp_f32_e32 v11, v11
	v_add_f32_e32 v12, v8, v12
	v_add_f32_e32 v12, v9, v12
	v_add_f32_e32 v12, v10, v12
	v_add_f32_e32 v116, v11, v12
	v_fmamk_f32 v12, v112, 0x3e38aa3b, v255
	v_fmamk_f32 v13, v113, 0x3e38aa3b, v255
	v_exp_f32_e32 v12, v12
	v_fmamk_f32 v14, v114, 0x3e38aa3b, v255
	v_exp_f32_e32 v13, v13
	v_fmamk_f32 v15, v115, 0x3e38aa3b, v255
	v_exp_f32_e32 v14, v14
	v_exp_f32_e32 v15, v15
	v_add_f32_e32 v116, v12, v116
	v_add_f32_e32 v116, v13, v116
	v_add_f32_e32 v116, v14, v116
	v_add_f32_e32 v116, v15, v116
; DI float quad_max(float v) { v = fmaxf(v, __shfl_xor(v, 16)); v = fmaxf(v, __shfl_xor(v, 32)); return v; }
; DI void softmax_tile(f32x4 (&st)[4], const bool (&msk)[4][4], float& m, float& l, f32x4 (&ot)[4]) {
;   float tm = -1e30f;
; #pragma unroll
;   for (int mt = 0; mt < 4; ++mt)
; #pragma unroll
;     for (int j = 0; j < 4; ++j) { float s = st[mt][j] * 0.125f; st[mt][j] = s; if (msk[mt][j]) tm = fmaxf(tm, s); }
;   tm = quad_max(tm);
;   float mn = fmaxf(m, tm);
;   float alpha = __expf(m - mn);
;   float ps = 0.f;
; #pragma unroll
;   for (int mt = 0; mt < 4; ++mt)
; #pragma unroll
;     for (int j = 0; j < 4; ++j) { float p = msk[mt][j] ? __expf(st[mt][j] - mn) : 0.f; st[mt][j] = p; ps += p; }
;   l = l * alpha + ps;
;   m = mn;
; DI void sel_attn_item(const Params& P, int it, u16* sQ, u16* sKunused, u16* sVunused) {
;     ...
;         bool msk[4][4];
; #pragma unroll
;         for (int mt = 0; mt < 4; ++mt)
; #pragma unroll
;           for (int j = 0; j < 4; ++j) { int s = kb * 64 + 16 * mt + 4 * quad + j; msk[mt][j] = selq && (s <= tq[qt]); }
;         softmax_tile(st, msk, m[qt], lsum[qt], ot[qt]);
.LBB0_252:
	s_andn2_b64 vcc, exec, s[2:3]
	s_cbranch_vccnz .LBB0_254
	v_cmp_le_i32_e32 vcc, v226, v168
	v_mul_f32_e32 v0, 0x3e000000, v128
	v_max_f32_e32 v0, 0xf149f2ca, v0
	s_and_b64 s[8:9], s[0:1], vcc
	v_cmp_lt_i32_e64 s[2:3], v226, v168
	v_cndmask_b32_e64 v0, v186, v0, s[8:9]
	v_mul_f32_e32 v1, 0x3e000000, v129
	v_max_f32_e32 v1, v0, v1
	s_and_b64 s[14:15], s[0:1], s[2:3]
	v_cmp_le_i32_e64 s[4:5], v226, v214
	v_cndmask_b32_e64 v0, v0, v1, s[14:15]
	v_mul_f32_e32 v1, 0x3e000000, v130
	v_max_f32_e32 v1, v0, v1
	s_and_b64 s[20:21], s[0:1], s[4:5]
	v_cmp_le_i32_e64 s[6:7], v226, v215
	v_cndmask_b32_e64 v0, v0, v1, s[20:21]
	v_mul_f32_e32 v1, 0x3e000000, v131
	v_max_f32_e32 v1, v0, v1
	s_and_b64 s[2:3], s[0:1], s[6:7]
	v_cmp_le_i32_e64 s[10:11], v226, v172
	v_cndmask_b32_e64 v0, v0, v1, s[2:3]
	v_mul_f32_e32 v1, 0x3e000000, v124
	v_max_f32_e32 v1, v0, v1
	s_and_b64 vcc, s[0:1], s[10:11]
	v_cndmask_b32_e32 v0, v0, v1, vcc
	v_cmp_lt_i32_e64 s[12:13], v226, v172
	v_mul_f32_e32 v1, 0x3e000000, v125
	v_max_f32_e32 v2, v0, v0
	v_max_f32_e32 v1, v2, v1
	s_and_b64 s[10:11], s[0:1], s[12:13]
	v_cndmask_b32_e64 v0, v0, v1, s[10:11]
	v_cmp_le_i32_e64 s[16:17], v232, v172
	v_mul_f32_e32 v1, 0x3e000000, v126
	v_max_f32_e32 v2, v0, v0
	v_max_f32_e32 v1, v2, v1
	s_and_b64 s[18:19], s[0:1], s[16:17]
	v_cndmask_b32_e64 v0, v0, v1, s[18:19]
	v_cmp_le_i32_e64 s[22:23], v231, v172
	v_mul_f32_e32 v1, 0x3e000000, v127
	v_max_f32_e32 v2, v0, v0
	v_max_f32_e32 v1, v2, v1
	s_and_b64 s[44:45], s[0:1], s[22:23]
	v_cndmask_b32_e64 v0, v0, v1, s[44:45]
	v_cmp_le_i32_e64 s[24:25], v230, v172
	v_mul_f32_e32 v1, 0x3e000000, v120
	v_max_f32_e32 v2, v0, v0
	v_max_f32_e32 v1, v2, v1
	s_and_b64 s[4:5], s[0:1], s[24:25]
	v_cndmask_b32_e64 v0, v0, v1, s[4:5]
	v_cmp_le_i32_e64 s[26:27], v229, v172
	v_mul_f32_e32 v1, 0x3e000000, v121
	v_max_f32_e32 v2, v0, v0
	v_max_f32_e32 v1, v2, v1
	s_and_b64 s[12:13], s[0:1], s[26:27]
	v_cndmask_b32_e64 v0, v0, v1, s[12:13]
	v_cmp_le_i32_e64 s[30:31], v228, v172
	v_mul_f32_e32 v1, 0x3e000000, v122
	v_max_f32_e32 v2, v0, v0
	v_max_f32_e32 v1, v2, v1
	s_and_b64 s[22:23], s[0:1], s[30:31]
	v_cndmask_b32_e64 v0, v0, v1, s[22:23]
	v_cmp_le_i32_e64 s[34:35], v227, v172
	v_mul_f32_e32 v1, 0x3e000000, v123
	v_max_f32_e32 v2, v0, v0
	v_max_f32_e32 v1, v2, v1
	s_and_b64 s[24:25], s[0:1], s[34:35]
	v_cndmask_b32_e64 v0, v0, v1, s[24:25]
	v_cmp_le_i32_e64 s[36:37], v225, v172
	v_mul_f32_e32 v1, 0x3e000000, v112
	v_max_f32_e32 v2, v0, v0
	v_max_f32_e32 v1, v2, v1
	s_and_b64 s[6:7], s[0:1], s[36:37]
	v_cndmask_b32_e64 v0, v0, v1, s[6:7]
	v_cmp_le_i32_e64 s[38:39], v224, v172
	v_mul_f32_e32 v1, 0x3e000000, v113
	v_max_f32_e32 v2, v0, v0
	v_max_f32_e32 v1, v2, v1
	s_and_b64 s[16:17], s[0:1], s[38:39]
	v_cndmask_b32_e64 v0, v0, v1, s[16:17]
	v_cmp_le_i32_e64 s[40:41], v223, v172
	v_mul_f32_e32 v1, 0x3e000000, v114
	v_max_f32_e32 v2, v0, v0
	v_max_f32_e32 v1, v2, v1
	s_and_b64 s[26:27], s[0:1], s[40:41]
	v_cndmask_b32_e64 v0, v0, v1, s[26:27]
	v_cmp_le_i32_e64 s[42:43], v222, v172
	v_mul_f32_e32 v1, 0x3e000000, v115
	v_max_f32_e32 v2, v0, v0
	v_max_f32_e32 v1, v2, v1
	s_and_b64 s[0:1], s[0:1], s[42:43]
	v_cndmask_b32_e64 v0, v0, v1, s[0:1]
	v_mbcnt_hi_u32_b32 v1, -1, v184
	v_and_b32_e32 v3, 64, v1
	v_xor_b32_e32 v2, 16, v1
	v_add_u32_e32 v3, 64, v3
	v_cmp_lt_i32_e64 s[30:31], v2, v3
	v_readlane_b32 s40, v246, 45
	v_readlane_b32 s41, v246, 46
	v_cndmask_b32_e64 v2, v1, v2, s[30:31]
	v_lshlrev_b32_e32 v2, 2, v2
	ds_bpermute_b32 v2, v2, v0
	v_max_f32_e32 v0, v0, v0
	s_waitcnt lgkmcnt(0)
	v_max_f32_e32 v2, v2, v2
	v_max_f32_e32 v0, v0, v2
	v_xor_b32_e32 v2, 32, v1
	v_cmp_lt_i32_e64 s[30:31], v2, v3
	s_nop 1
	v_cndmask_b32_e64 v1, v1, v2, s[30:31]
	v_lshlrev_b32_e32 v1, 2, v1
	ds_bpermute_b32 v1, v1, v0
	s_waitcnt lgkmcnt(0)
	v_max3_f32 v117, v218, v0, v1
	v_mul_f32_e32 v255, 0xbfb8aa3b, v117
	v_fmamk_f32 v0, v128, 0x3e38aa3b, v255
	v_fmamk_f32 v1, v129, 0x3e38aa3b, v255
	v_exp_f32_e32 v0, v0
	v_fmamk_f32 v2, v130, 0x3e38aa3b, v255
	v_exp_f32_e32 v1, v1
	v_fmamk_f32 v3, v131, 0x3e38aa3b, v255
	v_exp_f32_e32 v2, v2
	v_fmamk_f32 v4, v124, 0x3e38aa3b, v255
	v_exp_f32_e32 v3, v3
	v_fmamk_f32 v5, v125, 0x3e38aa3b, v255
	v_cndmask_b32_e64 v0, 0, v0, s[8:9]
	v_exp_f32_e32 v4, v4
	v_fmamk_f32 v6, v126, 0x3e38aa3b, v255
	v_cndmask_b32_e64 v1, 0, v1, s[14:15]
	v_exp_f32_e32 v5, v5
	v_fmamk_f32 v7, v127, 0x3e38aa3b, v255
	v_fmamk_f32 v12, v112, 0x3e38aa3b, v255
	v_add_f32_e32 v112, 0, v0
	v_cndmask_b32_e64 v2, 0, v2, s[20:21]
	v_exp_f32_e32 v6, v6
	v_fmamk_f32 v8, v120, 0x3e38aa3b, v255
	v_add_f32_e32 v112, v1, v112
	v_cndmask_b32_e64 v3, 0, v3, s[2:3]
	v_exp_f32_e32 v7, v7
	v_fmamk_f32 v9, v121, 0x3e38aa3b, v255
	v_add_f32_e32 v112, v2, v112
	v_cndmask_b32_e32 v4, 0, v4, vcc
	v_exp_f32_e32 v8, v8
	v_fmamk_f32 v10, v122, 0x3e38aa3b, v255
	v_add_f32_e32 v112, v3, v112
	v_cndmask_b32_e64 v5, 0, v5, s[10:11]
	v_exp_f32_e32 v9, v9
	v_fmamk_f32 v11, v123, 0x3e38aa3b, v255
	v_add_f32_e32 v112, v4, v112
	v_cndmask_b32_e64 v6, 0, v6, s[18:19]
	v_exp_f32_e32 v10, v10
	v_add_f32_e32 v112, v5, v112
	v_cndmask_b32_e64 v7, 0, v7, s[44:45]
	v_exp_f32_e32 v11, v11
	v_fmamk_f32 v13, v113, 0x3e38aa3b, v255
	v_add_f32_e32 v112, v6, v112
	v_cndmask_b32_e64 v8, 0, v8, s[4:5]
	v_exp_f32_e32 v12, v12
	v_fmamk_f32 v14, v114, 0x3e38aa3b, v255
	v_add_f32_e32 v112, v7, v112
	v_cndmask_b32_e64 v9, 0, v9, s[12:13]
	v_exp_f32_e32 v13, v13
	v_fmamk_f32 v15, v115, 0x3e38aa3b, v255
	v_add_f32_e32 v112, v8, v112
	v_cndmask_b32_e64 v10, 0, v10, s[22:23]
	v_exp_f32_e32 v14, v14
	v_add_f32_e32 v112, v9, v112
	v_cndmask_b32_e64 v11, 0, v11, s[24:25]
	v_exp_f32_e32 v15, v15
	v_add_f32_e32 v112, v10, v112
	v_cndmask_b32_e64 v12, 0, v12, s[6:7]
	v_add_f32_e32 v112, v11, v112
	v_cndmask_b32_e64 v13, 0, v13, s[16:17]
	v_add_f32_e32 v112, v12, v112
	v_cndmask_b32_e64 v14, 0, v14, s[26:27]
	v_add_f32_e32 v112, v13, v112
	v_cndmask_b32_e64 v15, 0, v15, s[0:1]
	v_add_f32_e32 v112, v14, v112
	v_add_f32_e32 v116, v15, v112

; DI void st_mma(f32x4 (&st)[4], const u16* sK, const bf16x8 (&bq)[2], int lane) {
;   const int r = lane & 15, quad = lane >> 4;
; #pragma unroll
;   for (int mt = 0; mt < 4; ++mt) {
;     f32x4 a = {0.f, 0.f, 0.f, 0.f};
; #pragma unroll
;     for (int ks = 0; ks < 2; ++ks) {
;       bf16x8 kf = *(const bf16x8*)(sK + (16 * mt + r) * 72 + ks * 32 + quad * 8);
;       a = __builtin_amdgcn_mfma_f32_16x16x32_bf16(kf, bq[ks], a, 0, 0, 0);
;     }
;     st[mt] = a;
;   }
; }
; DI void win_attn_item(const Params& P, int it, u16* sQ, u16* sKunused, u16* sVunused) {
;     ...
; #pragma unroll
;     for (int qt = 0; qt < 2; ++qt) {
;       f32x4 st[4];
;       st_mma(st, sK, bq[qt], lane);
;       const int tqlo = t0 + 16 * qt;
;       if (kb * 64 + 63 <= tqlo && tqlo + 15 - kb * 64 < 512) softmax_tile_full(st, m[qt], lsum[qt], ot[qt]);
;       else {
;         bool msk[4][4];
; #pragma unroll
;         for (int mt = 0; mt < 4; ++mt)
; #pragma unroll
;           for (int j = 0; j < 4; ++j) { int s = kb * 64 + 16 * mt + 4 * quad + j; int df = tq[qt] - s; msk[mt][j] = (df >= 0) && (df < 512); }
;         softmax_tile(st, msk, m[qt], lsum[qt], ot[qt]);
.LBB0_447:
	ds_read_b128 v[116:119], v170 offset:18432
	v_add_u32_e32 v10, 0x7000, v172
	ds_read_b128 v[120:123], v170 offset:18496
	ds_read_b128 v[124:127], v170 offset:20736
	ds_read_b128 v[128:131], v170 offset:20800
	ds_read_b128 v[132:135], v170 offset:23040
	ds_read_b128 v[112:115], v170 offset:23104
	ds_read2_b64 v[4:7], v10 offset0:160 offset1:164
	ds_read_b128 v[140:143], v171 offset:18432
	ds_read_b128 v[136:139], v171 offset:18496
	v_add_u32_e32 v13, 0x6800, v173
	s_sub_i32 s50, s49, 63
	s_waitcnt lgkmcnt(2)
	v_mov_b64_e32 v[104:105], v[6:7]
	ds_read2_b64 v[6:9], v13 offset0:136 offset1:140
	v_mov_b64_e32 v[106:107], v[4:5]
	v_mfma_f32_16x16x32_bf16 v[0:3], v[116:119], v[48:51], 0
	v_add_u32_e32 v12, 0x6800, v172
	v_add_u32_e32 v14, 0x7800, v172
	s_waitcnt lgkmcnt(0)
	v_mov_b64_e32 v[98:99], v[6:7]
	v_mfma_f32_16x16x32_bf16 v[156:159], v[120:123], v[52:55], v[0:3]
	v_mov_b64_e32 v[96:97], v[8:9]
	ds_read2_b64 v[8:11], v10 offset0:168 offset1:172
	ds_read2_b64 v[108:111], v12 offset0:128 offset1:132
	v_mfma_f32_16x16x32_bf16 v[0:3], v[124:127], v[48:51], 0
	ds_read2_b64 v[100:103], v14 offset0:200 offset1:204
	ds_read2_b64 v[80:83], v12 offset0:136 offset1:140
	ds_read2_b64 v[88:91], v14 offset0:192 offset1:196
	v_mfma_f32_16x16x32_bf16 v[152:155], v[128:131], v[52:55], v[0:3]
	s_cmp_le_u32 s49, s42
	s_cselect_b64 s[0:1], -1, 0
	s_cmp_gt_i32 s50, s46
	v_mfma_f32_16x16x32_bf16 v[0:3], v[132:135], v[48:51], 0
	s_cselect_b64 s[4:5], -1, 0
	s_and_b64 s[0:1], s[0:1], s[4:5]
	v_add_u32_e32 v217, 17, v174
	v_mfma_f32_16x16x32_bf16 v[4:7], v[140:143], v[48:51], 0
	v_add_u32_e32 v216, 15, v174
	v_add_u32_e32 v215, 14, v174
	v_add_u32_e32 v214, 1, v174
	v_mfma_f32_16x16x32_bf16 v[148:151], v[112:115], v[52:55], v[0:3]
	s_movk_i32 s6, 0x200
	v_add_u32_e32 v213, -1, v174
	v_add_u32_e32 v212, -2, v174
	ds_read2_b64 v[0:3], v13 offset0:128 offset1:132
	v_mfma_f32_16x16x32_bf16 v[144:147], v[136:139], v[52:55], v[4:7]
	v_add_u32_e32 v211, -15, v174
	v_add_u32_e32 v210, -16, v174
	v_subrev_u32_e32 v209, 17, v174
	v_subrev_u32_e32 v181, 18, v174
	s_waitcnt lgkmcnt(5)
	v_mov_b64_e32 v[92:93], v[10:11]
	v_mov_b64_e32 v[94:95], v[8:9]
	s_waitcnt lgkmcnt(0)
	v_mov_b64_e32 v[86:87], v[0:1]
	v_mov_b64_e32 v[84:85], v[2:3]
	s_mov_b64 s[22:23], -1
	s_andn2_b64 vcc, exec, s[0:1]
	v_add_u32_e32 v218, s49, v175
	v_cmp_gt_u32_e64 s[8:9], s6, v174
	v_cmp_gt_u32_e64 s[20:21], s6, v217
	v_cmp_gt_u32_e64 s[16:17], s6, v216
	v_cmp_gt_u32_e64 s[18:19], s6, v215
	v_cmp_gt_u32_e64 s[14:15], s6, v214
	v_cmp_gt_u32_e64 s[10:11], s6, v213
	v_cmp_gt_u32_e64 s[12:13], s6, v212
	v_cmp_gt_u32_e64 s[0:1], s6, v211
	v_cmp_gt_u32_e64 s[24:25], s6, v210
	v_cmp_gt_u32_e64 s[4:5], s6, v209
	v_cmp_gt_u32_e64 s[6:7], s6, v181
	s_cbranch_vccz .LBB0_449
	v_mul_f32_e32 v5, 0x3e000000, v156
	v_max_f32_e32 v5, 0xf149f2ca, v5
	v_subrev_u32_e32 v0, 63, v218
	v_cndmask_b32_e64 v5, v186, v5, s[20:21]
	v_mul_f32_e32 v6, 0x3e000000, v157
	s_movk_i32 s22, 0xfdff
	v_max_f32_e32 v6, v5, v6
	v_cmp_lt_u32_e64 s[26:27], s22, v0
	v_subrev_u32_e32 v1, 31, v174
	s_movk_i32 s30, 0x200
	v_cndmask_b32_e64 v0, v5, v6, s[26:27]
	v_mul_f32_e32 v5, 0x3e000000, v158
	v_max_f32_e32 v5, v0, v5
	v_cndmask_b32_e64 v0, v0, v5, s[16:17]
	v_mul_f32_e32 v5, 0x3e000000, v159
	v_max_f32_e32 v5, v0, v5
	v_cndmask_b32_e64 v0, v0, v5, s[18:19]
	v_mul_f32_e32 v5, 0x3e000000, v152
	v_max_f32_e32 v5, v0, v5
	v_cndmask_b32_e64 v0, v0, v5, s[14:15]
	v_mul_f32_e32 v5, 0x3e000000, v153
	v_max_f32_e32 v6, v0, v0
	v_max_f32_e32 v5, v6, v5
	v_cndmask_b32_e64 v0, v0, v5, s[8:9]
	v_mul_f32_e32 v5, 0x3e000000, v154
	v_max_f32_e32 v6, v0, v0
	v_max_f32_e32 v5, v6, v5
	v_cndmask_b32_e64 v0, v0, v5, s[10:11]
	v_mul_f32_e32 v5, 0x3e000000, v155
	v_max_f32_e32 v6, v0, v0
	v_max_f32_e32 v5, v6, v5
	v_cndmask_b32_e64 v0, v0, v5, s[12:13]
	v_mul_f32_e32 v5, 0x3e000000, v148
	v_max_f32_e32 v6, v0, v0
	v_max_f32_e32 v5, v6, v5
	v_cndmask_b32_e64 v0, v0, v5, s[0:1]
	v_mul_f32_e32 v5, 0x3e000000, v149
	v_max_f32_e32 v6, v0, v0
	v_max_f32_e32 v5, v6, v5
	v_cndmask_b32_e64 v0, v0, v5, s[24:25]
	v_mul_f32_e32 v5, 0x3e000000, v150
	v_max_f32_e32 v6, v0, v0
	v_max_f32_e32 v5, v6, v5
	v_cndmask_b32_e64 v0, v0, v5, s[4:5]
	v_mul_f32_e32 v5, 0x3e000000, v151
	v_max_f32_e32 v6, v0, v0
	v_max_f32_e32 v5, v6, v5
	v_cndmask_b32_e64 v0, v0, v5, s[6:7]
	v_mul_f32_e32 v5, 0x3e000000, v144
	v_max_f32_e32 v6, v0, v0
	v_max_f32_e32 v5, v6, v5
	v_cmp_gt_u32_e32 vcc, s30, v1
	v_subrev_u32_e32 v2, 32, v174
	v_mul_f32_e32 v1, 0x3e000000, v145
	v_cndmask_b32_e32 v0, v0, v5, vcc
	v_max_f32_e32 v5, v0, v0
	v_max_f32_e32 v1, v5, v1
	v_cmp_gt_u32_e64 s[22:23], s30, v2
	v_subrev_u32_e32 v3, 33, v174
	v_cmp_gt_u32_e64 s[28:29], s30, v3
	v_cndmask_b32_e64 v0, v0, v1, s[22:23]
	v_mul_f32_e32 v1, 0x3e000000, v146
	v_max_f32_e32 v2, v0, v0
	v_max_f32_e32 v1, v2, v1
	v_cndmask_b32_e64 v0, v0, v1, s[28:29]
	v_subrev_u32_e32 v4, 34, v174
	v_mul_f32_e32 v1, 0x3e000000, v147
	v_max_f32_e32 v2, v0, v0
	v_max_f32_e32 v1, v2, v1
	v_cmp_gt_u32_e64 s[30:31], s30, v4
	v_and_b32_e32 v2, 64, v185
	v_add_u32_e32 v2, 64, v2
	v_cndmask_b32_e64 v0, v0, v1, s[30:31]
	v_xor_b32_e32 v1, 16, v185
	v_cmp_lt_i32_e64 s[34:35], v1, v2
	s_nop 1
	v_cndmask_b32_e64 v1, v185, v1, s[34:35]
	v_lshlrev_b32_e32 v1, 2, v1
	ds_bpermute_b32 v1, v1, v0
	v_max_f32_e32 v0, v0, v0
	s_waitcnt lgkmcnt(0)
	v_max_f32_e32 v1, v1, v1
	v_max_f32_e32 v0, v0, v1
	v_xor_b32_e32 v1, 32, v185
	v_cmp_lt_i32_e64 s[34:35], v1, v2
	s_nop 1
	v_cndmask_b32_e64 v1, v185, v1, s[34:35]
	v_lshlrev_b32_e32 v1, 2, v1
	ds_bpermute_b32 v1, v1, v0
	s_waitcnt lgkmcnt(0)
; DI float quad_max(float v) { v = fmaxf(v, __shfl_xor(v, 16)); v = fmaxf(v, __shfl_xor(v, 32)); return v; }
; DI void softmax_tile(f32x4 (&st)[4], const bool (&msk)[4][4], float& m, float& l, f32x4 (&ot)[4]) {
;   float tm = -1e30f;
; #pragma unroll
;   for (int mt = 0; mt < 4; ++mt)
; #pragma unroll
;     for (int j = 0; j < 4; ++j) { float s = st[mt][j] * 0.125f; st[mt][j] = s; if (msk[mt][j]) tm = fmaxf(tm, s); }
;   tm = quad_max(tm);
;   float mn = fmaxf(m, tm);
;   float alpha = __expf(m - mn);
;   float ps = 0.f;
; #pragma unroll
;   for (int mt = 0; mt < 4; ++mt)
; #pragma unroll
;     for (int j = 0; j < 4; ++j) { float p = msk[mt][j] ? __expf(st[mt][j] - mn) : 0.f; st[mt][j] = p; ps += p; }
;   l = l * alpha + ps;
;   m = mn;
; DI void softmax_tile_full(f32x4 (&st)[4], float& m, float& l, f32x4 (&ot)[4]) {
;   float tm = st[0][0];
; #pragma unroll
;   for (int mt = 0; mt < 4; ++mt)
; #pragma unroll
;     for (int j = 0; j < 4; ++j) tm = fmaxf(tm, st[mt][j]);
;   tm = quad_max(tm) * 0.125f;
;   const float mn = fmaxf(m, tm);
;   const float alpha = __expf(m - mn);
;   float ps = 0.f;
; #pragma unroll
;   for (int mt = 0; mt < 4; ++mt)
; #pragma unroll
;     for (int j = 0; j < 4; ++j) { const float p = __expf(st[mt][j] * 0.125f - mn); st[mt][j] = p; ps += p; }
;   l = l * alpha + ps;
;   m = mn;
	v_max3_f32 v179, v180, v0, v1
	v_mul_f32_e32 v254, 0xbfb8aa3b, v179
	v_fmamk_f32 v0, v156, 0x3e38aa3b, v254
	v_fmamk_f32 v1, v157, 0x3e38aa3b, v254
	v_exp_f32_e32 v0, v0
	v_fmamk_f32 v2, v158, 0x3e38aa3b, v254
	v_exp_f32_e32 v1, v1
	v_fmamk_f32 v3, v159, 0x3e38aa3b, v254
	v_exp_f32_e32 v2, v2
	v_fmamk_f32 v4, v152, 0x3e38aa3b, v254
	v_exp_f32_e32 v3, v3
	v_fmamk_f32 v5, v153, 0x3e38aa3b, v254
	v_cndmask_b32_e64 v0, 0, v0, s[20:21]
	v_exp_f32_e32 v4, v4
	v_fmamk_f32 v6, v154, 0x3e38aa3b, v254
	v_cndmask_b32_e64 v1, 0, v1, s[26:27]
	v_exp_f32_e32 v5, v5
	v_fmamk_f32 v7, v155, 0x3e38aa3b, v254
	v_add_f32_e32 v162, 0, v0
	v_cndmask_b32_e64 v2, 0, v2, s[16:17]
	v_exp_f32_e32 v6, v6
	v_fmamk_f32 v8, v148, 0x3e38aa3b, v254
	v_add_f32_e32 v162, v1, v162
	v_cndmask_b32_e64 v3, 0, v3, s[18:19]
	v_exp_f32_e32 v7, v7
	v_fmamk_f32 v9, v149, 0x3e38aa3b, v254
	v_add_f32_e32 v162, v2, v162
	v_cndmask_b32_e64 v4, 0, v4, s[14:15]
	v_exp_f32_e32 v8, v8
	v_fmamk_f32 v10, v150, 0x3e38aa3b, v254
	v_add_f32_e32 v162, v3, v162
	v_cndmask_b32_e64 v5, 0, v5, s[8:9]
	v_exp_f32_e32 v9, v9
	v_fmamk_f32 v11, v151, 0x3e38aa3b, v254
	v_add_f32_e32 v162, v4, v162
	v_cndmask_b32_e64 v6, 0, v6, s[10:11]
	v_exp_f32_e32 v10, v10
	v_fmamk_f32 v12, v144, 0x3e38aa3b, v254
	v_add_f32_e32 v162, v5, v162
	v_cndmask_b32_e64 v7, 0, v7, s[12:13]
	v_exp_f32_e32 v11, v11
	v_fmamk_f32 v13, v145, 0x3e38aa3b, v254
	v_add_f32_e32 v162, v6, v162
	v_cndmask_b32_e64 v8, 0, v8, s[0:1]
	v_exp_f32_e32 v12, v12
	v_fmamk_f32 v14, v146, 0x3e38aa3b, v254
	v_add_f32_e32 v162, v7, v162
	v_cndmask_b32_e64 v9, 0, v9, s[24:25]
	v_exp_f32_e32 v13, v13
	v_fmamk_f32 v15, v147, 0x3e38aa3b, v254
	v_add_f32_e32 v162, v8, v162
	v_cndmask_b32_e64 v10, 0, v10, s[4:5]
	v_exp_f32_e32 v14, v14
	v_add_f32_e32 v162, v9, v162
	v_cndmask_b32_e64 v11, 0, v11, s[6:7]
	v_exp_f32_e32 v15, v15
	v_add_f32_e32 v162, v10, v162
	v_cndmask_b32_e32 v12, 0, v12, vcc
	v_add_f32_e32 v162, v11, v162
	v_cndmask_b32_e64 v13, 0, v13, s[22:23]
	v_add_f32_e32 v162, v12, v162
	v_cndmask_b32_e64 v14, 0, v14, s[28:29]
	v_add_f32_e32 v162, v13, v162
	v_cndmask_b32_e64 v15, 0, v15, s[30:31]
	v_add_f32_e32 v162, v14, v162
	v_add_f32_e32 v162, v15, v162
	s_mov_b64 s[22:23], 0
.LBB0_449:
	s_andn2_b64 vcc, exec, s[22:23]
	s_cbranch_vccnz .LBB0_451
	v_max_f32_e32 v0, v157, v157
	v_max_f32_e32 v1, v156, v156
	v_max_f32_e32 v0, v1, v0
	v_max3_f32 v0, v0, v158, v159
	v_max3_f32 v0, v0, v152, v153
	v_max3_f32 v0, v0, v154, v155
	v_and_b32_e32 v2, 64, v185
	v_max3_f32 v0, v0, v148, v149
	v_xor_b32_e32 v1, 16, v185
	v_add_u32_e32 v2, 64, v2
	v_max3_f32 v0, v0, v150, v151
	v_cmp_lt_i32_e32 vcc, v1, v2
	v_max3_f32 v0, v0, v144, v145
	v_max3_f32 v0, v0, v146, v147
	v_cndmask_b32_e32 v1, v185, v1, vcc
	v_lshlrev_b32_e32 v1, 2, v1
	ds_bpermute_b32 v1, v1, v0
	s_waitcnt lgkmcnt(0)
	v_max_f32_e32 v1, v1, v1
	v_max_f32_e32 v0, v0, v1
	v_xor_b32_e32 v1, 32, v185
	v_cmp_lt_i32_e32 vcc, v1, v2
	s_nop 1
	v_cndmask_b32_e32 v1, v185, v1, vcc
	v_lshlrev_b32_e32 v1, 2, v1
	ds_bpermute_b32 v1, v1, v0
	s_waitcnt lgkmcnt(0)
	v_max_f32_e32 v1, v1, v1
	v_max_f32_e32 v0, v0, v1
	v_mul_f32_e32 v0, 0x3e000000, v0
	v_max_f32_e32 v1, v180, v180
	v_max_f32_e32 v179, v1, v0
	v_mul_f32_e32 v254, 0xbfb8aa3b, v179
	v_fmamk_f32 v0, v156, 0x3e38aa3b, v254
	v_fmamk_f32 v1, v157, 0x3e38aa3b, v254
	v_exp_f32_e32 v0, v0
	v_fmamk_f32 v2, v158, 0x3e38aa3b, v254
	v_exp_f32_e32 v1, v1
	v_fmamk_f32 v3, v159, 0x3e38aa3b, v254
	v_exp_f32_e32 v2, v2
	v_exp_f32_e32 v3, v3
	v_add_f32_e32 v4, 0, v0
	v_add_f32_e32 v4, v1, v4
	v_add_f32_e32 v4, v2, v4
	v_add_f32_e32 v8, v3, v4
	v_fmamk_f32 v4, v152, 0x3e38aa3b, v254
	v_fmamk_f32 v5, v153, 0x3e38aa3b, v254
	v_exp_f32_e32 v4, v4
	v_fmamk_f32 v6, v154, 0x3e38aa3b, v254
	v_exp_f32_e32 v5, v5
	v_fmamk_f32 v7, v155, 0x3e38aa3b, v254
	v_exp_f32_e32 v6, v6
	v_exp_f32_e32 v7, v7
	v_add_f32_e32 v8, v4, v8
	v_add_f32_e32 v8, v5, v8
	v_add_f32_e32 v8, v6, v8
	v_add_f32_e32 v12, v7, v8
	v_fmamk_f32 v8, v148, 0x3e38aa3b, v254
	v_fmamk_f32 v9, v149, 0x3e38aa3b, v254
	v_exp_f32_e32 v8, v8
	v_fmamk_f32 v10, v150, 0x3e38aa3b, v254
	v_exp_f32_e32 v9, v9
	v_fmamk_f32 v11, v151, 0x3e38aa3b, v254
	v_exp_f32_e32 v10, v10
	v_exp_f32_e32 v11, v11
	v_add_f32_e32 v12, v8, v12
	v_add_f32_e32 v12, v9, v12
	v_add_f32_e32 v12, v10, v12
	v_add_f32_e32 v148, v11, v12
	v_fmamk_f32 v12, v144, 0x3e38aa3b, v254
	v_fmamk_f32 v13, v145, 0x3e38aa3b, v254
	v_exp_f32_e32 v12, v12
	v_fmamk_f32 v14, v146, 0x3e38aa3b, v254
	v_exp_f32_e32 v13, v13
	v_fmamk_f32 v15, v147, 0x3e38aa3b, v254
	v_exp_f32_e32 v14, v14
	v_exp_f32_e32 v15, v15
	v_add_f32_e32 v144, v12, v148
	v_add_f32_e32 v144, v13, v144
	v_add_f32_e32 v144, v14, v144
	v_add_f32_e32 v162, v15, v144
; DI unsigned pk2(float a, float b) { f32x2_t v = {a, b}; bf16x2_t r = __builtin_convertvector(v, bf16x2_t); return __builtin_bit_cast(unsigned, r); }
; DI void pv_mma(f32x4 (&ot)[4], const u16* sVt, const f32x4 (&p)[4], int lane) {
;   const int r = lane & 15, quad = lane >> 4;
; #pragma unroll
;   for (int ks = 0; ks < 2; ++ks) {
;     uint4 pu;
;     pu.x = pk2(p[2 * ks][0], p[2 * ks][1]); pu.y = pk2(p[2 * ks][2], p[2 * ks][3]);
;     pu.z = pk2(p[2 * ks + 1][0], p[2 * ks + 1][1]); pu.w = pk2(p[2 * ks + 1][2], p[2 * ks + 1][3]);
;     bf16x8 pb = __builtin_bit_cast(bf16x8, pu);
; #pragma unroll
;     for (int dt = 0; dt < 4; ++dt) {
;       const u16* vrow = sVt + (16 * dt + r) * 72;
;       s16x4 lo = *(const s16x4*)(vrow + ((32 * ks + 4 * quad) ^ (16 * dt)));
;       s16x4 hi = *(const s16x4*)(vrow + ((32 * ks + 16 + 4 * quad) ^ (16 * dt)));
;       bf16x8 vf = __builtin_shufflevector(lo, hi, 0, 1, 2, 3, 4, 5, 6, 7);
;       ot[dt] = __builtin_amdgcn_mfma_f32_16x16x32_bf16(vf, pb, ot[dt], 0, 0, 0);
;     }
;   }
; DI void win_attn_item(const Params& P, int it, u16* sQ, u16* sKunused, u16* sVunused) {
;     ...
;     for (int qt = 0; qt < 2; ++qt) {
;       f32x4 st[4];
;       st_mma(st, sK, bq[qt], lane);
;       const int tqlo = t0 + 16 * qt;
;       if (kb * 64 + 63 <= tqlo && tqlo + 15 - kb * 64 < 512) softmax_tile_full(st, m[qt], lsum[qt], ot[qt]);
;       else {
;         bool msk[4][4];
; #pragma unroll
;         for (int mt = 0; mt < 4; ++mt)
; #pragma unroll
;           for (int j = 0; j < 4; ++j) { int s = kb * 64 + 16 * mt + 4 * quad + j; int df = tq[qt] - s; msk[mt][j] = (df >= 0) && (df < 512); }
;         softmax_tile(st, msk, m[qt], lsum[qt], ot[qt]);
.LBB0_451:
	v_sub_f32_e32 v144, v180, v179
	v_mul_f32_e32 v144, 0x3fb8aa3b, v144
	v_exp_f32_e32 v148, v144
	v_cvt_pk_bf16_f32 v0, v0, v1
	v_cvt_pk_bf16_f32 v1, v2, v3
	v_cvt_pk_bf16_f32 v2, v4, v5
	v_pk_mul_f32 v[46:47], v[46:47], v[148:149] op_sel_hi:[1,0]
	v_pk_mul_f32 v[44:45], v[44:45], v[148:149] op_sel_hi:[1,0]
	v_cvt_pk_bf16_f32 v3, v6, v7
	v_pk_mul_f32 v[42:43], v[42:43], v[148:149] op_sel_hi:[1,0]
	v_pk_mul_f32 v[40:41], v[40:41], v[148:149] op_sel_hi:[1,0]
	v_pk_mul_f32 v[38:39], v[38:39], v[148:149] op_sel_hi:[1,0]
	v_pk_mul_f32 v[36:37], v[36:37], v[148:149] op_sel_hi:[1,0]
	v_pk_mul_f32 v[34:35], v[34:35], v[148:149] op_sel_hi:[1,0]
	v_pk_mul_f32 v[32:33], v[32:33], v[148:149] op_sel_hi:[1,0]
	v_mfma_f32_16x16x32_bf16 v[4:7], v[108:111], v[0:3], v[44:47]
	v_cvt_pk_bf16_f32 v8, v8, v9
	v_cvt_pk_bf16_f32 v9, v10, v11
	v_cvt_pk_bf16_f32 v10, v12, v13
	v_mfma_f32_16x16x32_bf16 v[40:43], v[104:107], v[0:3], v[40:43]
	v_cvt_pk_bf16_f32 v11, v14, v15
	s_cmp_le_u32 s49, s45
	s_cselect_b64 s[0:1], -1, 0
	v_mfma_f32_16x16x32_bf16 v[36:39], v[100:103], v[0:3], v[36:39]
	s_cmp_gt_i32 s50, s48
	s_cselect_b64 s[4:5], -1, 0
	s_and_b64 s[4:5], s[0:1], s[4:5]
	v_mfma_f32_16x16x32_bf16 v[0:3], v[96:99], v[0:3], v[32:35]
	s_mov_b64 s[0:1], -1
	s_and_b64 vcc, exec, s[4:5]
	v_mfma_f32_16x16x32_bf16 v[32:35], v[84:87], v[8:11], v[0:3]
	v_mfma_f32_16x16x32_bf16 v[0:3], v[116:119], v[56:59], 0
	v_mfma_f32_16x16x32_bf16 v[144:147], v[120:123], v[60:63], v[0:3]
	v_mfma_f32_16x16x32_bf16 v[0:3], v[124:127], v[56:59], 0
	v_mfma_f32_16x16x32_bf16 v[120:123], v[128:131], v[60:63], v[0:3]
	v_mfma_f32_16x16x32_bf16 v[0:3], v[132:135], v[56:59], 0
	v_mfma_f32_16x16x32_bf16 v[116:119], v[112:115], v[60:63], v[0:3]
	v_mfma_f32_16x16x32_bf16 v[112:115], v[140:143], v[56:59], 0
	v_mfma_f32_16x16x32_bf16 v[44:47], v[80:83], v[8:11], v[4:7]
	v_mfma_f32_16x16x32_bf16 v[40:43], v[92:95], v[8:11], v[40:43]
	v_mfma_f32_16x16x32_bf16 v[36:39], v[88:91], v[8:11], v[36:39]
	v_mfma_f32_16x16x32_bf16 v[112:115], v[136:139], v[60:63], v[112:115]
	s_cbranch_vccnz .LBB0_453
	s_nop 0
	v_add_u32_e32 v0, 33, v174
	v_mul_f32_e32 v5, 0x3e000000, v144
	s_movk_i32 s30, 0x200
	v_max_f32_e32 v5, 0xf149f2ca, v5
	v_cmp_gt_u32_e64 s[4:5], s30, v0
	v_add_u32_e32 v1, 0xffffffb1, v218
	s_movk_i32 s0, 0xfdff
	v_cndmask_b32_e64 v0, v186, v5, s[4:5]
	v_mul_f32_e32 v5, 0x3e000000, v145
	v_max_f32_e32 v5, v0, v5
	v_cmp_lt_u32_e64 s[10:11], s0, v1
	v_add_u32_e32 v2, 31, v174
	v_mul_f32_e32 v1, 0x3e000000, v146
	v_cndmask_b32_e64 v0, v0, v5, s[10:11]
	v_max_f32_e32 v1, v0, v1
	v_cmp_gt_u32_e64 s[18:19], s30, v2
	v_add_u32_e32 v3, 30, v174
	v_cmp_gt_u32_e64 s[20:21], s30, v3
	v_cndmask_b32_e64 v0, v0, v1, s[18:19]
	v_mul_f32_e32 v1, 0x3e000000, v147
	v_max_f32_e32 v1, v0, v1
	v_cndmask_b32_e64 v0, v0, v1, s[20:21]
	v_mul_f32_e32 v1, 0x3e000000, v120
	v_max_f32_e32 v1, v0, v1
	v_cmp_gt_u32_e32 vcc, s30, v217
	v_add_u32_e32 v4, 16, v174
	v_cmp_gt_u32_e64 s[6:7], s30, v4
	v_cndmask_b32_e32 v0, v0, v1, vcc
	v_mul_f32_e32 v1, 0x3e000000, v121
	v_max_f32_e32 v2, v0, v0
	v_max_f32_e32 v1, v2, v1
	v_cndmask_b32_e64 v0, v0, v1, s[6:7]
	v_mul_f32_e32 v1, 0x3e000000, v122
	v_max_f32_e32 v2, v0, v0
	v_max_f32_e32 v1, v2, v1
	v_cmp_gt_u32_e64 s[14:15], s30, v216
	v_cmp_gt_u32_e64 s[22:23], s30, v215
	v_cmp_gt_u32_e64 s[0:1], s30, v214
	v_cndmask_b32_e64 v0, v0, v1, s[14:15]
	v_mul_f32_e32 v1, 0x3e000000, v123
	v_max_f32_e32 v2, v0, v0
	v_max_f32_e32 v1, v2, v1
	v_cndmask_b32_e64 v0, v0, v1, s[22:23]
	v_mul_f32_e32 v1, 0x3e000000, v116
	v_max_f32_e32 v2, v0, v0
	v_max_f32_e32 v1, v2, v1
	v_cndmask_b32_e64 v0, v0, v1, s[0:1]
	v_mul_f32_e32 v1, 0x3e000000, v117
	v_max_f32_e32 v2, v0, v0
	v_max_f32_e32 v1, v2, v1
	v_cmp_gt_u32_e64 s[8:9], s30, v174
	v_cmp_gt_u32_e64 s[24:25], s30, v213
	v_cmp_gt_u32_e64 s[26:27], s30, v212
	v_cndmask_b32_e64 v0, v0, v1, s[8:9]
	v_mul_f32_e32 v1, 0x3e000000, v118
	v_max_f32_e32 v2, v0, v0
	v_max_f32_e32 v1, v2, v1
	v_cndmask_b32_e64 v0, v0, v1, s[24:25]
	v_mul_f32_e32 v1, 0x3e000000, v119
	v_max_f32_e32 v2, v0, v0
	v_max_f32_e32 v1, v2, v1
	v_cndmask_b32_e64 v0, v0, v1, s[26:27]
	v_mul_f32_e32 v1, 0x3e000000, v112
	v_max_f32_e32 v2, v0, v0
	v_max_f32_e32 v1, v2, v1
	v_cmp_gt_u32_e64 s[16:17], s30, v211
	v_cmp_gt_u32_e64 s[12:13], s30, v210
	v_cmp_gt_u32_e64 s[28:29], s30, v209
	v_cndmask_b32_e64 v0, v0, v1, s[16:17]
	v_mul_f32_e32 v1, 0x3e000000, v113
	v_max_f32_e32 v2, v0, v0
	v_max_f32_e32 v1, v2, v1
	v_cndmask_b32_e64 v0, v0, v1, s[12:13]
	v_mul_f32_e32 v1, 0x3e000000, v114
	v_max_f32_e32 v2, v0, v0
	v_max_f32_e32 v1, v2, v1
	v_cndmask_b32_e64 v0, v0, v1, s[28:29]
	v_mul_f32_e32 v1, 0x3e000000, v115
	v_max_f32_e32 v2, v0, v0
	v_max_f32_e32 v1, v2, v1
	v_cmp_gt_u32_e64 s[30:31], s30, v181
	v_and_b32_e32 v2, 64, v185
	v_add_u32_e32 v2, 64, v2
	v_cndmask_b32_e64 v0, v0, v1, s[30:31]
	v_xor_b32_e32 v1, 16, v185
	v_cmp_lt_i32_e64 s[34:35], v1, v2
	s_nop 1
	v_cndmask_b32_e64 v1, v185, v1, s[34:35]
	v_lshlrev_b32_e32 v1, 2, v1
	ds_bpermute_b32 v1, v1, v0
	v_max_f32_e32 v0, v0, v0
	s_waitcnt lgkmcnt(0)
; DI float quad_max(float v) { v = fmaxf(v, __shfl_xor(v, 16)); v = fmaxf(v, __shfl_xor(v, 32)); return v; }
; DI void softmax_tile(f32x4 (&st)[4], const bool (&msk)[4][4], float& m, float& l, f32x4 (&ot)[4]) {
;   float tm = -1e30f;
; #pragma unroll
;   for (int mt = 0; mt < 4; ++mt)
; #pragma unroll
;     for (int j = 0; j < 4; ++j) { float s = st[mt][j] * 0.125f; st[mt][j] = s; if (msk[mt][j]) tm = fmaxf(tm, s); }
;   tm = quad_max(tm);
;   float mn = fmaxf(m, tm);
;   float alpha = __expf(m - mn);
;   float ps = 0.f;
; #pragma unroll
;   for (int mt = 0; mt < 4; ++mt)
; #pragma unroll
;     for (int j = 0; j < 4; ++j) { float p = msk[mt][j] ? __expf(st[mt][j] - mn) : 0.f; st[mt][j] = p; ps += p; }
;   l = l * alpha + ps;
;   m = mn;
; DI void softmax_tile_full(f32x4 (&st)[4], float& m, float& l, f32x4 (&ot)[4]) {
;   float tm = st[0][0];
; #pragma unroll
;   for (int mt = 0; mt < 4; ++mt)
; #pragma unroll
;     for (int j = 0; j < 4; ++j) tm = fmaxf(tm, st[mt][j]);
;   tm = quad_max(tm) * 0.125f;
;   const float mn = fmaxf(m, tm);
;   const float alpha = __expf(m - mn);
;   float ps = 0.f;
; #pragma unroll
;   for (int mt = 0; mt < 4; ++mt)
; #pragma unroll
;     for (int j = 0; j < 4; ++j) { const float p = __expf(st[mt][j] * 0.125f - mn); st[mt][j] = p; ps += p; }
;   l = l * alpha + ps;
;   m = mn;
	v_max_f32_e32 v1, v1, v1
	v_max_f32_e32 v0, v0, v1
	v_xor_b32_e32 v1, 32, v185
	v_cmp_lt_i32_e64 s[34:35], v1, v2
	s_nop 1
	v_cndmask_b32_e64 v1, v185, v1, s[34:35]
	v_lshlrev_b32_e32 v1, 2, v1
	ds_bpermute_b32 v1, v1, v0
	s_waitcnt lgkmcnt(0)
	v_max3_f32 v125, v177, v0, v1
	v_mul_f32_e32 v255, 0xbfb8aa3b, v125
	v_fmamk_f32 v0, v144, 0x3e38aa3b, v255
	v_fmamk_f32 v1, v145, 0x3e38aa3b, v255
	v_exp_f32_e32 v0, v0
	v_fmamk_f32 v2, v146, 0x3e38aa3b, v255
	v_exp_f32_e32 v1, v1
	v_fmamk_f32 v3, v147, 0x3e38aa3b, v255
	v_exp_f32_e32 v2, v2
	v_fmamk_f32 v4, v120, 0x3e38aa3b, v255
	v_exp_f32_e32 v3, v3
	v_fmamk_f32 v5, v121, 0x3e38aa3b, v255
	v_cndmask_b32_e64 v0, 0, v0, s[4:5]
	v_exp_f32_e32 v4, v4
	v_fmamk_f32 v6, v122, 0x3e38aa3b, v255
	v_cndmask_b32_e64 v1, 0, v1, s[10:11]
	v_exp_f32_e32 v5, v5
	v_fmamk_f32 v7, v123, 0x3e38aa3b, v255
	v_add_f32_e32 v124, 0, v0
	v_cndmask_b32_e64 v2, 0, v2, s[18:19]
	v_exp_f32_e32 v6, v6
	v_fmamk_f32 v8, v116, 0x3e38aa3b, v255
	v_add_f32_e32 v124, v1, v124
	v_cndmask_b32_e64 v3, 0, v3, s[20:21]
	v_exp_f32_e32 v7, v7
	v_fmamk_f32 v9, v117, 0x3e38aa3b, v255
	v_add_f32_e32 v124, v2, v124
	v_cndmask_b32_e32 v4, 0, v4, vcc
	v_exp_f32_e32 v8, v8
	v_fmamk_f32 v10, v118, 0x3e38aa3b, v255
	v_add_f32_e32 v124, v3, v124
	v_cndmask_b32_e64 v5, 0, v5, s[6:7]
	v_exp_f32_e32 v9, v9
	v_fmamk_f32 v11, v119, 0x3e38aa3b, v255
	v_add_f32_e32 v124, v4, v124
	v_cndmask_b32_e64 v6, 0, v6, s[14:15]
	v_exp_f32_e32 v10, v10
	v_fmamk_f32 v12, v112, 0x3e38aa3b, v255
	v_add_f32_e32 v124, v5, v124
	v_cndmask_b32_e64 v7, 0, v7, s[22:23]
	v_exp_f32_e32 v11, v11
	v_fmamk_f32 v13, v113, 0x3e38aa3b, v255
	v_add_f32_e32 v124, v6, v124
	v_cndmask_b32_e64 v8, 0, v8, s[0:1]
	v_exp_f32_e32 v12, v12
	v_fmamk_f32 v14, v114, 0x3e38aa3b, v255
	v_add_f32_e32 v124, v7, v124
	v_cndmask_b32_e64 v9, 0, v9, s[8:9]
	v_exp_f32_e32 v13, v13
	v_fmamk_f32 v15, v115, 0x3e38aa3b, v255
	v_add_f32_e32 v124, v8, v124
	v_cndmask_b32_e64 v10, 0, v10, s[24:25]
	v_exp_f32_e32 v14, v14
	v_add_f32_e32 v124, v9, v124
	v_cndmask_b32_e64 v11, 0, v11, s[26:27]
	v_exp_f32_e32 v15, v15
	v_add_f32_e32 v124, v10, v124
	v_cndmask_b32_e64 v12, 0, v12, s[16:17]
	v_add_f32_e32 v124, v11, v124
	v_cndmask_b32_e64 v13, 0, v13, s[12:13]
	v_add_f32_e32 v124, v12, v124
	v_cndmask_b32_e64 v14, 0, v14, s[28:29]
	v_add_f32_e32 v124, v13, v124
	v_cndmask_b32_e64 v15, 0, v15, s[30:31]
	v_add_f32_e32 v124, v14, v124
	v_add_f32_e32 v124, v15, v124
	s_mov_b64 s[0:1], 0
.LBB0_453:
	s_andn2_b64 vcc, exec, s[0:1]
	s_cbranch_vccnz .LBB0_455
	v_max_f32_e32 v0, v145, v145
	v_max_f32_e32 v1, v144, v144
	v_max_f32_e32 v0, v1, v0
	v_max3_f32 v0, v0, v146, v147
	v_max3_f32 v0, v0, v120, v121
	v_max3_f32 v0, v0, v122, v123
	v_and_b32_e32 v2, 64, v185
	v_max3_f32 v0, v0, v116, v117
	v_xor_b32_e32 v1, 16, v185
	v_add_u32_e32 v2, 64, v2
	v_max3_f32 v0, v0, v118, v119
	v_cmp_lt_i32_e32 vcc, v1, v2
	v_max3_f32 v0, v0, v112, v113
	v_max3_f32 v0, v0, v114, v115
	v_cndmask_b32_e32 v1, v185, v1, vcc
	v_lshlrev_b32_e32 v1, 2, v1
	ds_bpermute_b32 v1, v1, v0
	s_waitcnt lgkmcnt(0)
	v_max_f32_e32 v1, v1, v1
	v_max_f32_e32 v0, v0, v1
	v_xor_b32_e32 v1, 32, v185
	v_cmp_lt_i32_e32 vcc, v1, v2
	s_nop 1
	v_cndmask_b32_e32 v1, v185, v1, vcc
	v_lshlrev_b32_e32 v1, 2, v1
	ds_bpermute_b32 v1, v1, v0
	s_waitcnt lgkmcnt(0)
	v_max_f32_e32 v1, v1, v1
	v_max_f32_e32 v0, v0, v1
	v_mul_f32_e32 v0, 0x3e000000, v0
	v_max_f32_e32 v1, v177, v177
	v_max_f32_e32 v125, v1, v0
	v_mul_f32_e32 v255, 0xbfb8aa3b, v125
	v_fmamk_f32 v0, v144, 0x3e38aa3b, v255
	v_fmamk_f32 v1, v145, 0x3e38aa3b, v255
	v_exp_f32_e32 v0, v0
	v_fmamk_f32 v2, v146, 0x3e38aa3b, v255
	v_exp_f32_e32 v1, v1
	v_fmamk_f32 v3, v147, 0x3e38aa3b, v255
	v_exp_f32_e32 v2, v2
	v_exp_f32_e32 v3, v3
	v_add_f32_e32 v4, 0, v0
	v_add_f32_e32 v4, v1, v4
	v_add_f32_e32 v4, v2, v4
	v_add_f32_e32 v8, v3, v4
	v_fmamk_f32 v4, v120, 0x3e38aa3b, v255
	v_fmamk_f32 v5, v121, 0x3e38aa3b, v255
	v_exp_f32_e32 v4, v4
	v_fmamk_f32 v6, v122, 0x3e38aa3b, v255
	v_exp_f32_e32 v5, v5
	v_fmamk_f32 v7, v123, 0x3e38aa3b, v255
	v_exp_f32_e32 v6, v6
	v_exp_f32_e32 v7, v7
	v_add_f32_e32 v8, v4, v8
	v_add_f32_e32 v8, v5, v8
	v_add_f32_e32 v8, v6, v8
	v_add_f32_e32 v12, v7, v8
	v_fmamk_f32 v8, v116, 0x3e38aa3b, v255
	v_fmamk_f32 v9, v117, 0x3e38aa3b, v255
	v_exp_f32_e32 v8, v8
	v_fmamk_f32 v10, v118, 0x3e38aa3b, v255
	v_exp_f32_e32 v9, v9
	v_fmamk_f32 v11, v119, 0x3e38aa3b, v255
	v_exp_f32_e32 v10, v10
	v_exp_f32_e32 v11, v11
	v_add_f32_e32 v12, v8, v12
	v_add_f32_e32 v12, v9, v12
	v_add_f32_e32 v12, v10, v12
	v_add_f32_e32 v116, v11, v12
	v_fmamk_f32 v12, v112, 0x3e38aa3b, v255
	v_fmamk_f32 v13, v113, 0x3e38aa3b, v255
	v_exp_f32_e32 v12, v12
	v_fmamk_f32 v14, v114, 0x3e38aa3b, v255
	v_exp_f32_e32 v13, v13
	v_fmamk_f32 v15, v115, 0x3e38aa3b, v255
	v_exp_f32_e32 v14, v14
	v_exp_f32_e32 v15, v15
	v_add_f32_e32 v112, v12, v116
	v_add_f32_e32 v112, v13, v112
	v_add_f32_e32 v112, v14, v112
	v_add_f32_e32 v124, v15, v112
